# A/B of strategy 4: the static s_setprio 1 given to waves 0-3 (the half running one barrier ahead) instead of waves 4-7
# speedup vs baseline: 1.0011x; 1.0002x over previous
;     ...
;         const bool has_next = S.next(ui + 1, nxt);
;         const unsigned nA = has_next ? nxt.ao : cA, nB = has_next ? nxt.bo : cB;
;         const int nt = cur.nt;
;     ...
;         for (int a = 0; a < 2; ++a)
; #pragma unroll
;             for (int b = 0; b < 2; ++b)
; #pragma unroll
;                 for (int m = 0; m < 4; ++m)
; #pragma unroll
;                     for (int n = 0; n < 2; ++n) acc[a][b][m][n] = (f32x4){0.f, 0.f, 0.f, 0.f};
;         cur = nxt; cA = nA; cB = nB; ++ui;
.LBB0_278:
	s_xor_b64 s[36:37], s[4:5], -1
	s_and_b64 s[4:5], s[4:5], exec
	v_mov_b32_e32 v2, 0
	s_cselect_b32 s4, s90, s11
	s_cselect_b32 s5, s91, s10
	s_add_i32 s8, s11, 0x100080
	s_add_i32 s9, s10, 0x100
	s_mov_b32 s10, -2
	v_mov_b32_e32 v3, v2
	v_mov_b32_e32 v4, v2
	v_mov_b32_e32 v5, v2
	v_mov_b32_e32 v6, v2
	v_mov_b32_e32 v7, v2
	v_mov_b32_e32 v8, v2
	v_mov_b32_e32 v9, v2
	v_mov_b32_e32 v18, v2
	v_mov_b32_e32 v19, v2
	v_mov_b32_e32 v20, v2
	v_mov_b32_e32 v21, v2
	v_mov_b32_e32 v22, v2
	v_mov_b32_e32 v23, v2
	v_mov_b32_e32 v24, v2
	v_mov_b32_e32 v25, v2
	v_mov_b32_e32 v34, v2
	v_mov_b32_e32 v35, v2
	v_mov_b32_e32 v36, v2
	v_mov_b32_e32 v37, v2
	v_mov_b32_e32 v38, v2
	v_mov_b32_e32 v39, v2
	v_mov_b32_e32 v40, v2
	v_mov_b32_e32 v41, v2
	v_mov_b32_e32 v50, v2
	v_mov_b32_e32 v51, v2
	v_mov_b32_e32 v52, v2
	v_mov_b32_e32 v53, v2
	v_mov_b32_e32 v54, v2
	v_mov_b32_e32 v55, v2
	v_mov_b32_e32 v56, v2
	v_mov_b32_e32 v57, v2
	v_mov_b32_e32 v10, v2
	v_mov_b32_e32 v11, v2
	v_mov_b32_e32 v12, v2
	v_mov_b32_e32 v13, v2
	v_mov_b32_e32 v14, v2
	v_mov_b32_e32 v15, v2
	v_mov_b32_e32 v16, v2
	v_mov_b32_e32 v17, v2
	v_mov_b32_e32 v26, v2
	v_mov_b32_e32 v27, v2
	v_mov_b32_e32 v28, v2
	v_mov_b32_e32 v29, v2
	v_mov_b32_e32 v30, v2
	v_mov_b32_e32 v31, v2
	v_mov_b32_e32 v32, v2
	v_mov_b32_e32 v33, v2
	v_mov_b32_e32 v42, v2
	v_mov_b32_e32 v43, v2
	v_mov_b32_e32 v44, v2
	v_mov_b32_e32 v45, v2
	v_mov_b32_e32 v46, v2
	v_mov_b32_e32 v47, v2
	v_mov_b32_e32 v48, v2
	v_mov_b32_e32 v49, v2
	v_mov_b32_e32 v58, v2
	v_mov_b32_e32 v59, v2
	v_mov_b32_e32 v60, v2
	v_mov_b32_e32 v61, v2
	v_mov_b32_e32 v62, v2
	v_mov_b32_e32 v63, v2
	v_mov_b32_e32 v64, v2
	v_mov_b32_e32 v65, v2
	v_mov_b32_e32 v66, v2
	v_mov_b32_e32 v67, v2
	v_mov_b32_e32 v68, v2
	v_mov_b32_e32 v69, v2
	v_mov_b32_e32 v70, v2
	v_mov_b32_e32 v71, v2
	v_mov_b32_e32 v72, v2
	v_mov_b32_e32 v73, v2
	v_mov_b32_e32 v82, v2
	v_mov_b32_e32 v83, v2
	v_mov_b32_e32 v84, v2
	v_mov_b32_e32 v85, v2
	v_mov_b32_e32 v86, v2
	v_mov_b32_e32 v87, v2
	v_mov_b32_e32 v88, v2
	v_mov_b32_e32 v89, v2
	v_mov_b32_e32 v98, v2
	v_mov_b32_e32 v99, v2
	v_mov_b32_e32 v100, v2
	v_mov_b32_e32 v101, v2
	v_mov_b32_e32 v102, v2
	v_mov_b32_e32 v103, v2
	v_mov_b32_e32 v104, v2
	v_mov_b32_e32 v105, v2
	v_mov_b32_e32 v114, v2
	v_mov_b32_e32 v115, v2
	v_mov_b32_e32 v116, v2
	v_mov_b32_e32 v117, v2
	v_mov_b32_e32 v118, v2
	v_mov_b32_e32 v119, v2
	v_mov_b32_e32 v120, v2
	v_mov_b32_e32 v121, v2
	v_mov_b32_e32 v74, v2
	v_mov_b32_e32 v75, v2
	v_mov_b32_e32 v76, v2
	v_mov_b32_e32 v77, v2
	v_mov_b32_e32 v78, v2
	v_mov_b32_e32 v79, v2
	v_mov_b32_e32 v80, v2
	v_mov_b32_e32 v81, v2
	v_mov_b32_e32 v90, v2
	v_mov_b32_e32 v91, v2
	v_mov_b32_e32 v92, v2
	v_mov_b32_e32 v93, v2
	v_mov_b32_e32 v94, v2
	v_mov_b32_e32 v95, v2
	v_mov_b32_e32 v96, v2
	v_mov_b32_e32 v97, v2
	v_mov_b32_e32 v106, v2
	v_mov_b32_e32 v107, v2
	v_mov_b32_e32 v108, v2
	v_mov_b32_e32 v109, v2
	v_mov_b32_e32 v110, v2
	v_mov_b32_e32 v111, v2
	v_mov_b32_e32 v112, v2
	v_mov_b32_e32 v113, v2
	v_mov_b32_e32 v122, v2
	v_mov_b32_e32 v123, v2
	v_mov_b32_e32 v124, v2
	v_mov_b32_e32 v125, v2
	v_mov_b32_e32 v126, v2
	v_mov_b32_e32 v127, v2
	v_mov_b32_e32 v128, v2
	v_mov_b32_e32 v129, v2
	v_readlane_b32 s98, v255, 4
	s_nop 3
	s_cmp_lg_u32 s98, 0
	s_cbranch_scc1 .Lprio_skip_0
	s_setprio 1

;     ...
;         const bool has_next = S.next(ui + 1, nxt);
;         const unsigned nA = has_next ? nxt.ao : cA, nB = has_next ? nxt.bo : cB;
;         const int nt = cur.nt;
;     ...
;         for (int a = 0; a < 2; ++a)
; #pragma unroll
;             for (int b = 0; b < 2; ++b)
; #pragma unroll
;                 for (int m = 0; m < 4; ++m)
; #pragma unroll
;                     for (int n = 0; n < 2; ++n) acc[a][b][m][n] = (f32x4){0.f, 0.f, 0.f, 0.f};
;         cur = nxt; cA = nA; cB = nB; ++ui;
.LBB0_558:
	v_mov_b32_e32 v2, 0
	s_add_i32 s44, s44, 0x80080
	s_addk_i32 s45, 0x100
	s_mov_b32 s46, -2
	v_mov_b32_e32 v3, v2
	v_mov_b32_e32 v4, v2
	v_mov_b32_e32 v5, v2
	v_mov_b32_e32 v6, v2
	v_mov_b32_e32 v7, v2
	v_mov_b32_e32 v8, v2
	v_mov_b32_e32 v9, v2
	v_mov_b32_e32 v18, v2
	v_mov_b32_e32 v19, v2
	v_mov_b32_e32 v20, v2
	v_mov_b32_e32 v21, v2
	v_mov_b32_e32 v22, v2
	v_mov_b32_e32 v23, v2
	v_mov_b32_e32 v24, v2
	v_mov_b32_e32 v25, v2
	v_mov_b32_e32 v34, v2
	v_mov_b32_e32 v35, v2
	v_mov_b32_e32 v36, v2
	v_mov_b32_e32 v37, v2
	v_mov_b32_e32 v38, v2
	v_mov_b32_e32 v39, v2
	v_mov_b32_e32 v40, v2
	v_mov_b32_e32 v41, v2
	v_mov_b32_e32 v50, v2
	v_mov_b32_e32 v51, v2
	v_mov_b32_e32 v52, v2
	v_mov_b32_e32 v53, v2
	v_mov_b32_e32 v54, v2
	v_mov_b32_e32 v55, v2
	v_mov_b32_e32 v56, v2
	v_mov_b32_e32 v57, v2
	v_mov_b32_e32 v10, v2
	v_mov_b32_e32 v11, v2
	v_mov_b32_e32 v12, v2
	v_mov_b32_e32 v13, v2
	v_mov_b32_e32 v14, v2
	v_mov_b32_e32 v15, v2
	v_mov_b32_e32 v16, v2
	v_mov_b32_e32 v17, v2
	v_mov_b32_e32 v26, v2
	v_mov_b32_e32 v27, v2
	v_mov_b32_e32 v28, v2
	v_mov_b32_e32 v29, v2
	v_mov_b32_e32 v30, v2
	v_mov_b32_e32 v31, v2
	v_mov_b32_e32 v32, v2
	v_mov_b32_e32 v33, v2
	v_mov_b32_e32 v42, v2
	v_mov_b32_e32 v43, v2
	v_mov_b32_e32 v44, v2
	v_mov_b32_e32 v45, v2
	v_mov_b32_e32 v46, v2
	v_mov_b32_e32 v47, v2
	v_mov_b32_e32 v48, v2
	v_mov_b32_e32 v49, v2
	v_mov_b32_e32 v58, v2
	v_mov_b32_e32 v59, v2
	v_mov_b32_e32 v60, v2
	v_mov_b32_e32 v61, v2
	v_mov_b32_e32 v62, v2
	v_mov_b32_e32 v63, v2
	v_mov_b32_e32 v64, v2
	v_mov_b32_e32 v65, v2
	v_mov_b32_e32 v66, v2
	v_mov_b32_e32 v67, v2
	v_mov_b32_e32 v68, v2
	v_mov_b32_e32 v69, v2
	v_mov_b32_e32 v70, v2
	v_mov_b32_e32 v71, v2
	v_mov_b32_e32 v72, v2
	v_mov_b32_e32 v73, v2
	v_mov_b32_e32 v82, v2
	v_mov_b32_e32 v83, v2
	v_mov_b32_e32 v84, v2
	v_mov_b32_e32 v85, v2
	v_mov_b32_e32 v86, v2
	v_mov_b32_e32 v87, v2
	v_mov_b32_e32 v88, v2
	v_mov_b32_e32 v89, v2
	v_mov_b32_e32 v98, v2
	v_mov_b32_e32 v99, v2
	v_mov_b32_e32 v100, v2
	v_mov_b32_e32 v101, v2
	v_mov_b32_e32 v102, v2
	v_mov_b32_e32 v103, v2
	v_mov_b32_e32 v104, v2
	v_mov_b32_e32 v105, v2
	v_mov_b32_e32 v114, v2
	v_mov_b32_e32 v115, v2
	v_mov_b32_e32 v116, v2
	v_mov_b32_e32 v117, v2
	v_mov_b32_e32 v118, v2
	v_mov_b32_e32 v119, v2
	v_mov_b32_e32 v120, v2
	v_mov_b32_e32 v121, v2
	v_mov_b32_e32 v74, v2
	v_mov_b32_e32 v75, v2
	v_mov_b32_e32 v76, v2
	v_mov_b32_e32 v77, v2
	v_mov_b32_e32 v78, v2
	v_mov_b32_e32 v79, v2
	v_mov_b32_e32 v80, v2
	v_mov_b32_e32 v81, v2
	v_mov_b32_e32 v90, v2
	v_mov_b32_e32 v91, v2
	v_mov_b32_e32 v92, v2
	v_mov_b32_e32 v93, v2
	v_mov_b32_e32 v94, v2
	v_mov_b32_e32 v95, v2
	v_mov_b32_e32 v96, v2
	v_mov_b32_e32 v97, v2
	v_mov_b32_e32 v106, v2
	v_mov_b32_e32 v107, v2
	v_mov_b32_e32 v108, v2
	v_mov_b32_e32 v109, v2
	v_mov_b32_e32 v110, v2
	v_mov_b32_e32 v111, v2
	v_mov_b32_e32 v112, v2
	v_mov_b32_e32 v113, v2
	v_mov_b32_e32 v122, v2
	v_mov_b32_e32 v123, v2
	v_mov_b32_e32 v124, v2
	v_mov_b32_e32 v125, v2
	v_mov_b32_e32 v126, v2
	v_mov_b32_e32 v127, v2
	v_mov_b32_e32 v128, v2
	v_mov_b32_e32 v129, v2
	v_readlane_b32 s98, v255, 4
	s_nop 3
	s_cmp_lg_u32 s98, 0
	s_cbranch_scc1 .Lprio_skip_1
	s_setprio 1

;     ...
;         const bool has_next = S.next(ui + 1, nxt);
;         const unsigned nA = has_next ? nxt.ao : cA, nB = has_next ? nxt.bo : cB;
;         const int nt = cur.nt;
;     ...
;         for (int a = 0; a < 2; ++a)
; #pragma unroll
;             for (int b = 0; b < 2; ++b)
; #pragma unroll
;                 for (int m = 0; m < 4; ++m)
; #pragma unroll
;                     for (int n = 0; n < 2; ++n) acc[a][b][m][n] = (f32x4){0.f, 0.f, 0.f, 0.f};
;         cur = nxt; cA = nA; cB = nB; ++ui;
.LBB0_861:
	v_mov_b32_e32 v2, 0
	s_add_i32 s10, s10, 0x100080
	s_addk_i32 s11, 0x100
	s_mov_b32 s18, -2
	v_mov_b32_e32 v3, v2
	v_mov_b32_e32 v4, v2
	v_mov_b32_e32 v5, v2
	v_mov_b32_e32 v6, v2
	v_mov_b32_e32 v7, v2
	v_mov_b32_e32 v8, v2
	v_mov_b32_e32 v9, v2
	v_mov_b32_e32 v18, v2
	v_mov_b32_e32 v19, v2
	v_mov_b32_e32 v20, v2
	v_mov_b32_e32 v21, v2
	v_mov_b32_e32 v22, v2
	v_mov_b32_e32 v23, v2
	v_mov_b32_e32 v24, v2
	v_mov_b32_e32 v25, v2
	v_mov_b32_e32 v34, v2
	v_mov_b32_e32 v35, v2
	v_mov_b32_e32 v36, v2
	v_mov_b32_e32 v37, v2
	v_mov_b32_e32 v38, v2
	v_mov_b32_e32 v39, v2
	v_mov_b32_e32 v40, v2
	v_mov_b32_e32 v41, v2
	v_mov_b32_e32 v50, v2
	v_mov_b32_e32 v51, v2
	v_mov_b32_e32 v52, v2
	v_mov_b32_e32 v53, v2
	v_mov_b32_e32 v54, v2
	v_mov_b32_e32 v55, v2
	v_mov_b32_e32 v56, v2
	v_mov_b32_e32 v57, v2
	v_mov_b32_e32 v10, v2
	v_mov_b32_e32 v11, v2
	v_mov_b32_e32 v12, v2
	v_mov_b32_e32 v13, v2
	v_mov_b32_e32 v14, v2
	v_mov_b32_e32 v15, v2
	v_mov_b32_e32 v16, v2
	v_mov_b32_e32 v17, v2
	v_mov_b32_e32 v26, v2
	v_mov_b32_e32 v27, v2
	v_mov_b32_e32 v28, v2
	v_mov_b32_e32 v29, v2
	v_mov_b32_e32 v30, v2
	v_mov_b32_e32 v31, v2
	v_mov_b32_e32 v32, v2
	v_mov_b32_e32 v33, v2
	v_mov_b32_e32 v42, v2
	v_mov_b32_e32 v43, v2
	v_mov_b32_e32 v44, v2
	v_mov_b32_e32 v45, v2
	v_mov_b32_e32 v46, v2
	v_mov_b32_e32 v47, v2
	v_mov_b32_e32 v48, v2
	v_mov_b32_e32 v49, v2
	v_mov_b32_e32 v58, v2
	v_mov_b32_e32 v59, v2
	v_mov_b32_e32 v60, v2
	v_mov_b32_e32 v61, v2
	v_mov_b32_e32 v62, v2
	v_mov_b32_e32 v63, v2
	v_mov_b32_e32 v64, v2
	v_mov_b32_e32 v65, v2
	v_mov_b32_e32 v66, v2
	v_mov_b32_e32 v67, v2
	v_mov_b32_e32 v68, v2
	v_mov_b32_e32 v69, v2
	v_mov_b32_e32 v70, v2
	v_mov_b32_e32 v71, v2
	v_mov_b32_e32 v72, v2
	v_mov_b32_e32 v73, v2
	v_mov_b32_e32 v82, v2
	v_mov_b32_e32 v83, v2
	v_mov_b32_e32 v84, v2
	v_mov_b32_e32 v85, v2
	v_mov_b32_e32 v86, v2
	v_mov_b32_e32 v87, v2
	v_mov_b32_e32 v88, v2
	v_mov_b32_e32 v89, v2
	v_mov_b32_e32 v98, v2
	v_mov_b32_e32 v99, v2
	v_mov_b32_e32 v100, v2
	v_mov_b32_e32 v101, v2
	v_mov_b32_e32 v102, v2
	v_mov_b32_e32 v103, v2
	v_mov_b32_e32 v104, v2
	v_mov_b32_e32 v105, v2
	v_mov_b32_e32 v114, v2
	v_mov_b32_e32 v115, v2
	v_mov_b32_e32 v116, v2
	v_mov_b32_e32 v117, v2
	v_mov_b32_e32 v118, v2
	v_mov_b32_e32 v119, v2
	v_mov_b32_e32 v120, v2
	v_mov_b32_e32 v121, v2
	v_mov_b32_e32 v74, v2
	v_mov_b32_e32 v75, v2
	v_mov_b32_e32 v76, v2
	v_mov_b32_e32 v77, v2
	v_mov_b32_e32 v78, v2
	v_mov_b32_e32 v79, v2
	v_mov_b32_e32 v80, v2
	v_mov_b32_e32 v81, v2
	v_mov_b32_e32 v90, v2
	v_mov_b32_e32 v91, v2
	v_mov_b32_e32 v92, v2
	v_mov_b32_e32 v93, v2
	v_mov_b32_e32 v94, v2
	v_mov_b32_e32 v95, v2
	v_mov_b32_e32 v96, v2
	v_mov_b32_e32 v97, v2
	v_mov_b32_e32 v106, v2
	v_mov_b32_e32 v107, v2
	v_mov_b32_e32 v108, v2
	v_mov_b32_e32 v109, v2
	v_mov_b32_e32 v110, v2
	v_mov_b32_e32 v111, v2
	v_mov_b32_e32 v112, v2
	v_mov_b32_e32 v113, v2
	v_mov_b32_e32 v122, v2
	v_mov_b32_e32 v123, v2
	v_mov_b32_e32 v124, v2
	v_mov_b32_e32 v125, v2
	v_mov_b32_e32 v126, v2
	v_mov_b32_e32 v127, v2
	v_mov_b32_e32 v128, v2
	v_mov_b32_e32 v129, v2
	v_readlane_b32 s98, v255, 4
	s_nop 3
	s_cmp_lg_u32 s98, 0
	s_cbranch_scc1 .Lprio_skip_2
	s_setprio 1
